# additionally: wave-wide sum-of-squares reductions in the norm phases and rw_mix done with DPP row scans + v_readlane instead of six dependent ds_bpermute round trips
# speedup vs baseline: 1.0078x; 1.0019x over previous
; DI unsigned pk2(float lo, float hi) { return f2bf(lo) | (f2bf(hi) << 16); }
; #define BIDX() sgpr_opaque((int)__builtin_amdgcn_workgroup_id_x())
; DI const float* modp(const unsigned char* ws, int layer, int who, int idx) { return (const float*)(ws + WS_MOD) + ((size_t)(layer * 9 + who) * 6 + idx) * D; }
; DI void phase_norm(int layer, const float* g, int sidx, bf16_t* dst, bool first) {
;     ...
;     for (int m0 = BIDX() * 8 + wave; m0 < M; m0 += 2 * nw) {
;         const int m1 = m0 + nw; const bool has1 = m1 < M; const int m1c = has1 ? m1 : m0;
;         const float* z0 = zrow_src(zcs, zls, m0); const float* z1 = zrow_src(zcs, zls, m1c);
;         f32x4 v0[4], v1[4]; float ss0 = 0.f, ss1 = 0.f;
; #pragma unroll
;         for (int j = 0; j < 4; ++j) { v0[j] = *(const f32x4*)(z0 + 4 * lane + 256 * j); v1[j] = *(const f32x4*)(z1 + 4 * lane + 256 * j); }
; #pragma unroll
;         for (int j = 0; j < 4; ++j) { ss0 += v0[j][0] * v0[j][0] + v0[j][1] * v0[j][1] + v0[j][2] * v0[j][2] + v0[j][3] * v0[j][3]; ss1 += v1[j][0] * v1[j][0] + v1[j][1] * v1[j][1] + v1[j][2] * v1[j][2] + v1[j][3] * v1[j][3]; }
; #pragma unroll
;         for (int o = 1; o < 64; o <<= 1) { ss0 += __shfl_xor(ss0, o); ss1 += __shfl_xor(ss1, o); }
; #pragma unroll
;         for (int r = 0; r < 2; ++r) {
;             if (r == 1 && !has1) break;
;             const int m = r ? m1 : m0; const int b = m / T, t = m - b * T; const int who = t < LC ? 8 : b;
;             const float* sh = modp(ws, layer, who, sidx); const float* sc = modp(ws, layer, who, sidx + 1);
;             const float rstd = rsqrtf((r ? ss1 : ss0) * (1.f / D) + 1e-6f);
; #pragma unroll
;             for (int j = 0; j < 4; ++j) { const int c = 4 * lane + 256 * j;
;                 const f32x4 gg = *(const f32x4*)(g + c), s1 = *(const f32x4*)(sc + c), s0 = *(const f32x4*)(sh + c);
;                 f32x4 y = (r ? v1[j] : v0[j]) * rstd * gg; y = y * (s1 + 1.f) + s0;
;                 u32x2 w; w.x = pk2(y[0], y[1]); w.y = pk2(y[2], y[3]);
;                 *(u32x2*)(dst + (size_t)m * D + c) = w; }
.LBB0_51:
	s_mov_b32 s2, 0x78787879
	v_mul_hi_i32 v0, v30, s2
	v_lshrrev_b32_e32 v2, 31, v0
	v_ashrrev_i32_e32 v0, 11, v0
	v_add_u32_e32 v5, v0, v2
	s_movk_i32 s2, 0xef00
	v_mad_i32_i24 v0, v5, s2, v30
	s_movk_i32 s2, 0x100
	v_cmp_gt_i32_e64 s[4:5], s2, v0
	s_movk_i32 s2, 0xff
	v_cmp_lt_i32_e32 vcc, s2, v0
	v_mov_b64_e32 v[6:7], s[12:13]
	s_and_saveexec_b64 s[2:3], vcc
	s_xor_b64 s[2:3], exec, s[2:3]
	v_mul_i32_i24_e32 v0, 0xffffef00, v5
	v_lshl_add_u32 v0, v5, 12, v0
	s_movk_i32 s6, 0xff00
	v_add3_u32 v8, v30, v0, s6
	v_mov_b64_e32 v[6:7], s[14:15]
	s_andn2_saveexec_b64 s[2:3], s[2:3]
	v_lshl_add_u32 v8, v5, 8, v0
	s_or_b64 exec, exec, s[2:3]
	v_add_u32_e32 v46, s24, v30
	s_mov_b32 s2, 0x8800
	v_cmp_gt_i32_e32 vcc, s2, v46
	s_mov_b32 s2, 0x78787879
	s_nop 0
	v_cndmask_b32_e32 v2, v30, v46, vcc
	v_mul_hi_i32 v0, v2, s2
	v_lshrrev_b32_e32 v3, 31, v0
	v_ashrrev_i32_e32 v0, 11, v0
	v_add_u32_e32 v0, v0, v3
	s_movk_i32 s2, 0xef00
	v_mad_i32_i24 v9, v0, s2, v2
	s_movk_i32 s2, 0xff
	v_cmp_lt_i32_e64 s[6:7], s2, v9
	v_mov_b64_e32 v[2:3], s[12:13]
	s_and_saveexec_b64 s[2:3], s[6:7]
	s_xor_b64 s[2:3], exec, s[2:3]
	v_lshlrev_b32_e32 v0, 12, v0
	s_movk_i32 s6, 0xff00
	v_add3_u32 v4, v0, v9, s6
	v_mov_b64_e32 v[2:3], s[14:15]
	s_andn2_saveexec_b64 s[2:3], s[2:3]
	v_lshl_add_u32 v4, v0, 8, v9
	s_or_b64 exec, exec, s[2:3]
	v_ashrrev_i32_e32 v9, 31, v8
	v_lshlrev_b64 v[8:9], 12, v[8:9]
	v_lshl_add_u64 v[6:7], v[6:7], 0, v[8:9]
	v_lshlrev_b32_e32 v0, 2, v32
	v_lshl_add_u64 v[6:7], v[6:7], 0, v[0:1]
	global_load_dwordx4 v[56:59], v[6:7], off
	global_load_dwordx4 v[26:29], v[6:7], off offset:1024
	s_waitcnt lgkmcnt(0)
	global_load_dwordx4 v[14:17], v[6:7], off offset:2048
	s_nop 0
	global_load_dwordx4 v[6:9], v[6:7], off offset:3072
	v_cndmask_b32_e64 v5, v5, 8, s[4:5]
	v_add_u32_e32 v5, s25, v5
	v_mul_i32_i24_e32 v10, 6, v5
	v_ashrrev_i32_e32 v11, 31, v10
	v_lshlrev_b64 v[10:11], 12, v[10:11]
	v_lshl_add_u64 v[10:11], s[16:17], 0, v[10:11]
	s_mov_b64 s[2:3], 0x4000
	v_lshl_add_u64 v[48:49], v[10:11], 0, s[2:3]
	s_mov_b64 s[2:3], 0x3000
	v_lshl_add_u64 v[12:13], v[48:49], 0, v[0:1]
	v_lshl_add_u64 v[72:73], v[10:11], 0, s[2:3]
	global_load_dwordx4 v[60:63], v[12:13], off
	global_load_dwordx4 v[64:67], v[34:35], off
	v_lshl_add_u64 v[10:11], v[72:73], 0, v[0:1]
	global_load_dwordx4 v[68:71], v[10:11], off
	s_mov_b32 s2, 0x800000
	v_mov_b32_e32 v41, v1
	s_waitcnt vmcnt(0)
	v_mov_b32_e32 v12, v57
	v_mov_b32_e32 v13, v27
	v_mov_b32_e32 v10, v56
	v_mov_b32_e32 v11, v26
	v_mov_b32_e32 v24, v15
	v_mov_b32_e32 v25, v7
	v_pk_mul_f32 v[12:13], v[12:13], v[12:13]
	v_mov_b32_e32 v18, v58
	v_mov_b32_e32 v19, v28
	v_mov_b32_e32 v22, v14
	v_mov_b32_e32 v23, v6
	v_pk_mul_f32 v[24:25], v[24:25], v[24:25]
	v_pk_fma_f32 v[10:11], v[10:11], v[10:11], v[12:13]
	v_mov_b32_e32 v20, v59
	v_mov_b32_e32 v21, v29
	v_mov_b32_e32 v74, v16
	v_mov_b32_e32 v75, v8
	v_pk_fma_f32 v[12:13], v[22:23], v[22:23], v[24:25]
	v_pk_fma_f32 v[10:11], v[18:19], v[18:19], v[10:11]
	v_mov_b32_e32 v76, v17
	v_mov_b32_e32 v77, v9
	v_pk_fma_f32 v[12:13], v[74:75], v[74:75], v[12:13]
	v_pk_fma_f32 v[10:11], v[20:21], v[20:21], v[10:11]
	v_pk_fma_f32 v[12:13], v[76:77], v[76:77], v[12:13]
	v_add_f32_e32 v5, v10, v11
	v_add_f32_e32 v5, v5, v12
	v_add_f32_e32 v5, v5, v13
	v_mov_b32_e32 v96, v5
	s_nop 1
	v_add_f32_dpp v96, v96, v96 row_shr:1 row_mask:0xf bank_mask:0xf
	s_nop 1
	v_add_f32_dpp v96, v96, v96 row_shr:2 row_mask:0xf bank_mask:0xf
	s_nop 1
	v_add_f32_dpp v96, v96, v96 row_shr:4 row_mask:0xf bank_mask:0xf
	s_nop 1
	v_add_f32_dpp v96, v96, v96 row_shr:8 row_mask:0xf bank_mask:0xf
	s_nop 1
	v_add_f32_dpp v96, v96, v96 row_bcast:15 row_mask:0xa bank_mask:0xf
	s_nop 1
	v_add_f32_dpp v96, v96, v96 row_bcast:31 row_mask:0xc bank_mask:0xf
	s_nop 0
	v_readlane_b32 s26, v96, 63
	v_pk_add_f32 v[62:63], v[62:63], 1.0 op_sel_hi:[1,0]
	v_pk_add_f32 v[60:61], v[60:61], 1.0 op_sel_hi:[1,0]
	v_ashrrev_i32_e32 v5, 31, v4
	v_lshlrev_b64 v[4:5], 12, v[4:5]
	v_lshl_add_u64 v[2:3], v[2:3], 0, v[4:5]
	v_lshl_add_u64 v[2:3], v[2:3], 0, v[0:1]
	global_load_dwordx4 v[22:25], v[2:3], off
	global_load_dwordx4 v[18:21], v[2:3], off offset:1024
	s_nop 1
	v_mov_b32_e32 v4, s26
	v_fmamk_f32 v4, v4, 0x3a800000, v183
	v_mul_f32_e32 v5, 0x4b800000, v4
	v_cmp_gt_f32_e64 s[4:5], s2, v4
	s_nop 1
	v_cndmask_b32_e64 v4, v4, v5, s[4:5]
	v_rsq_f32_e32 v31, v4
	global_load_dwordx4 v[10:13], v[2:3], off offset:2048
	s_nop 0
	global_load_dwordx4 v[2:5], v[2:3], off offset:3072
	v_mul_f32_e32 v43, 0x45800000, v31
	v_cndmask_b32_e64 v74, v31, v43, s[4:5]
	v_pk_mul_f32 v[58:59], v[58:59], v[74:75] op_sel_hi:[1,0]
	v_pk_mul_f32 v[56:57], v[56:57], v[74:75] op_sel_hi:[1,0]
	v_pk_mul_f32 v[58:59], v[66:67], v[58:59]
	v_pk_mul_f32 v[56:57], v[64:65], v[56:57]
	v_pk_fma_f32 v[58:59], v[62:63], v[58:59], v[70:71]
	v_pk_fma_f32 v[56:57], v[60:61], v[56:57], v[68:69]
	v_bfe_u32 v45, v58, 16, 1
	v_bfe_u32 v31, v56, 16, 1
	v_bfe_u32 v43, v57, 16, 1
	v_bfe_u32 v47, v59, 16, 1
	v_add3_u32 v31, v56, v31, s31
	v_add3_u32 v45, v58, v45, s31
	v_add3_u32 v43, v57, v43, s31
	v_add3_u32 v47, v59, v47, s31
	v_lshrrev_b32_e32 v31, 16, v31
	v_lshrrev_b32_e32 v45, 16, v45
	v_and_or_b32 v56, v43, s0, v31
	v_and_or_b32 v57, v47, s0, v45
	global_store_dwordx2 v[38:39], v[56:57], off
	v_lshl_add_u64 v[60:61], v[48:49], 0, v[40:41]
	global_load_dwordx4 v[56:59], v[34:35], off offset:1024
	v_lshl_add_u64 v[64:65], v[72:73], 0, v[40:41]
	global_load_dwordx4 v[60:63], v[60:61], off
	v_pk_mul_f32 v[28:29], v[28:29], v[74:75] op_sel_hi:[1,0]
	global_load_dwordx4 v[64:67], v[64:65], off
	v_pk_mul_f32 v[26:27], v[26:27], v[74:75] op_sel_hi:[1,0]
	v_mov_b32_e32 v43, v1
	v_pk_mul_f32 v[16:17], v[16:17], v[74:75] op_sel_hi:[1,0]
	v_pk_mul_f32 v[14:15], v[14:15], v[74:75] op_sel_hi:[1,0]
	v_pk_mul_f32 v[8:9], v[8:9], v[74:75] op_sel_hi:[1,0]
	v_pk_mul_f32 v[6:7], v[6:7], v[74:75] op_sel_hi:[1,0]
	s_waitcnt vmcnt(2)
; DI unsigned pk2(float lo, float hi) { return f2bf(lo) | (f2bf(hi) << 16); }
; DI const float* modp(const unsigned char* ws, int layer, int who, int idx) { return (const float*)(ws + WS_MOD) + ((size_t)(layer * 9 + who) * 6 + idx) * D; }
; DI void phase_norm(int layer, const float* g, int sidx, bf16_t* dst, bool first) {
;     ...
;         for (int j = 0; j < 4; ++j) { v0[j] = *(const f32x4*)(z0 + 4 * lane + 256 * j); v1[j] = *(const f32x4*)(z1 + 4 * lane + 256 * j); }
; #pragma unroll
;         for (int j = 0; j < 4; ++j) { ss0 += v0[j][0] * v0[j][0] + v0[j][1] * v0[j][1] + v0[j][2] * v0[j][2] + v0[j][3] * v0[j][3]; ss1 += v1[j][0] * v1[j][0] + v1[j][1] * v1[j][1] + v1[j][2] * v1[j][2] + v1[j][3] * v1[j][3]; }
; #pragma unroll
;         for (int o = 1; o < 64; o <<= 1) { ss0 += __shfl_xor(ss0, o); ss1 += __shfl_xor(ss1, o); }
; #pragma unroll
;         for (int r = 0; r < 2; ++r) {
;             if (r == 1 && !has1) break;
;             const int m = r ? m1 : m0; const int b = m / T, t = m - b * T; const int who = t < LC ? 8 : b;
;             const float* sh = modp(ws, layer, who, sidx); const float* sc = modp(ws, layer, who, sidx + 1);
;             const float rstd = rsqrtf((r ? ss1 : ss0) * (1.f / D) + 1e-6f);
; #pragma unroll
;             for (int j = 0; j < 4; ++j) { const int c = 4 * lane + 256 * j;
;                 const f32x4 gg = *(const f32x4*)(g + c), s1 = *(const f32x4*)(sc + c), s0 = *(const f32x4*)(sh + c);
;                 f32x4 y = (r ? v1[j] : v0[j]) * rstd * gg; y = y * (s1 + 1.f) + s0;
;                 u32x2 w; w.x = pk2(y[0], y[1]); w.y = pk2(y[2], y[3]);
;                 *(u32x2*)(dst + (size_t)m * D + c) = w; }
	v_pk_mul_f32 v[26:27], v[56:57], v[26:27]
	v_pk_mul_f32 v[28:29], v[58:59], v[28:29]
	s_waitcnt vmcnt(1)
	v_pk_add_f32 v[56:57], v[62:63], 1.0 op_sel_hi:[1,0]
	v_pk_add_f32 v[58:59], v[60:61], 1.0 op_sel_hi:[1,0]
	s_waitcnt vmcnt(0)
	v_pk_fma_f32 v[28:29], v[56:57], v[28:29], v[66:67]
	v_pk_fma_f32 v[26:27], v[58:59], v[26:27], v[64:65]
	v_bfe_u32 v47, v28, 16, 1
	v_bfe_u32 v31, v26, 16, 1
	v_bfe_u32 v45, v27, 16, 1
	v_bfe_u32 v55, v29, 16, 1
	v_add3_u32 v26, v26, v31, s31
	v_add3_u32 v28, v28, v47, s31
	v_add3_u32 v27, v27, v45, s31
	v_add3_u32 v29, v29, v55, s31
	v_lshrrev_b32_e32 v26, 16, v26
	v_lshrrev_b32_e32 v28, 16, v28
	v_and_or_b32 v26, v27, s0, v26
	v_and_or_b32 v27, v29, s0, v28
	global_store_dwordx2 v[38:39], v[26:27], off offset:512
	v_lshl_add_u64 v[56:57], v[48:49], 0, v[42:43]
	global_load_dwordx4 v[26:29], v[34:35], off offset:2048
	v_lshl_add_u64 v[60:61], v[72:73], 0, v[42:43]
	global_load_dwordx4 v[56:59], v[56:57], off
	v_mov_b32_e32 v45, v1
	global_load_dwordx4 v[60:63], v[60:61], off
	s_waitcnt vmcnt(2)
	v_pk_mul_f32 v[14:15], v[26:27], v[14:15]
	v_pk_mul_f32 v[16:17], v[28:29], v[16:17]
	s_waitcnt vmcnt(1)
	v_pk_add_f32 v[26:27], v[58:59], 1.0 op_sel_hi:[1,0]
	v_pk_add_f32 v[28:29], v[56:57], 1.0 op_sel_hi:[1,0]
	s_waitcnt vmcnt(0)
	v_pk_fma_f32 v[16:17], v[26:27], v[16:17], v[62:63]
	v_pk_fma_f32 v[14:15], v[28:29], v[14:15], v[60:61]
	v_bfe_u32 v28, v16, 16, 1
	v_bfe_u32 v26, v14, 16, 1
	v_bfe_u32 v27, v15, 16, 1
	v_bfe_u32 v29, v17, 16, 1
	v_add3_u32 v14, v14, v26, s31
	v_add3_u32 v16, v16, v28, s31
	v_add3_u32 v15, v15, v27, s31
	v_add3_u32 v17, v17, v29, s31
	v_lshrrev_b32_e32 v14, 16, v14
	v_lshrrev_b32_e32 v16, 16, v16
	v_and_or_b32 v14, v15, s0, v14
	v_and_or_b32 v15, v17, s0, v16
	global_store_dwordx2 v[38:39], v[14:15], off offset:1024
	v_lshl_add_u64 v[14:15], v[48:49], 0, v[44:45]
	global_load_dwordx4 v[26:29], v[34:35], off offset:3072
	global_load_dwordx4 v[56:59], v[14:15], off
	v_lshl_add_u64 v[14:15], v[72:73], 0, v[44:45]
	global_load_dwordx4 v[60:63], v[14:15], off
	v_mul_f32_e32 v14, v23, v23
	v_mul_f32_e32 v15, v19, v19
	v_mul_f32_e32 v16, v11, v11
	v_fmac_f32_e32 v14, v22, v22
	v_fmac_f32_e32 v15, v18, v18
	v_mul_f32_e32 v17, v3, v3
	v_fmac_f32_e32 v16, v10, v10
	v_fmac_f32_e32 v14, v24, v24
	v_fmac_f32_e32 v15, v20, v20
	v_fmac_f32_e32 v17, v2, v2
	v_fmac_f32_e32 v16, v12, v12
	v_fmac_f32_e32 v14, v25, v25
	v_fmac_f32_e32 v15, v21, v21
	v_fmac_f32_e32 v17, v4, v4
	v_fmac_f32_e32 v16, v13, v13
	v_add_f32_e32 v14, v14, v15
	v_fmac_f32_e32 v17, v5, v5
	v_add_f32_e32 v14, v14, v16
	v_add_f32_e32 v14, v14, v17
	v_mov_b32_e32 v96, v14
	s_nop 1
	v_add_f32_dpp v96, v96, v96 row_shr:1 row_mask:0xf bank_mask:0xf
	s_nop 1
	v_add_f32_dpp v96, v96, v96 row_shr:2 row_mask:0xf bank_mask:0xf
	s_nop 1
	v_add_f32_dpp v96, v96, v96 row_shr:4 row_mask:0xf bank_mask:0xf
	s_nop 1
	v_add_f32_dpp v96, v96, v96 row_shr:8 row_mask:0xf bank_mask:0xf
	s_nop 1
	v_add_f32_dpp v96, v96, v96 row_bcast:15 row_mask:0xa bank_mask:0xf
	s_nop 1
	v_add_f32_dpp v96, v96, v96 row_bcast:31 row_mask:0xc bank_mask:0xf
	s_nop 0
	v_readlane_b32 s26, v96, 63
	s_waitcnt vmcnt(2)
	v_pk_mul_f32 v[6:7], v[6:7], v[26:27]
	v_pk_mul_f32 v[8:9], v[8:9], v[28:29]
	s_waitcnt vmcnt(1)
	v_pk_add_f32 v[16:17], v[58:59], 1.0 op_sel_hi:[1,0]
	v_pk_add_f32 v[26:27], v[56:57], 1.0 op_sel_hi:[1,0]
	s_waitcnt vmcnt(0)
	v_pk_fma_f32 v[8:9], v[8:9], v[16:17], v[62:63]
	v_pk_fma_f32 v[6:7], v[6:7], v[26:27], v[60:61]
	v_bfe_u32 v26, v8, 16, 1
	v_bfe_u32 v16, v6, 16, 1
	v_bfe_u32 v17, v7, 16, 1
	v_bfe_u32 v27, v9, 16, 1
	v_add3_u32 v6, v6, v16, s31
	v_add3_u32 v8, v8, v26, s31
	v_add3_u32 v7, v7, v17, s31
	v_add3_u32 v9, v9, v27, s31
	v_lshrrev_b32_e32 v6, 16, v6
	v_lshrrev_b32_e32 v8, 16, v8
	v_and_or_b32 v6, v7, s0, v6
	v_and_or_b32 v7, v9, s0, v8
	global_store_dwordx2 v[38:39], v[6:7], off offset:1536
	s_and_saveexec_b64 s[4:5], vcc
	s_cbranch_execz .LBB0_50
; DI unsigned pk2(float lo, float hi) { return f2bf(lo) | (f2bf(hi) << 16); }
; DI const float* modp(const unsigned char* ws, int layer, int who, int idx) { return (const float*)(ws + WS_MOD) + ((size_t)(layer * 9 + who) * 6 + idx) * D; }
; DI void phase_norm(int layer, const float* g, int sidx, bf16_t* dst, bool first) {
;     ...
;         for (int r = 0; r < 2; ++r) {
;             if (r == 1 && !has1) break;
;             const int m = r ? m1 : m0; const int b = m / T, t = m - b * T; const int who = t < LC ? 8 : b;
;             const float* sh = modp(ws, layer, who, sidx); const float* sc = modp(ws, layer, who, sidx + 1);
;             const float rstd = rsqrtf((r ? ss1 : ss0) * (1.f / D) + 1e-6f);
; #pragma unroll
;             for (int j = 0; j < 4; ++j) { const int c = 4 * lane + 256 * j;
;                 const f32x4 gg = *(const f32x4*)(g + c), s1 = *(const f32x4*)(sc + c), s0 = *(const f32x4*)(sh + c);
;                 f32x4 y = (r ? v1[j] : v0[j]) * rstd * gg; y = y * (s1 + 1.f) + s0;
;                 u32x2 w; w.x = pk2(y[0], y[1]); w.y = pk2(y[2], y[3]);
;                 *(u32x2*)(dst + (size_t)m * D + c) = w; }
	s_mov_b32 s2, 0x78787879
	v_mul_hi_i32 v6, v46, s2
	v_lshrrev_b32_e32 v7, 31, v6
	v_ashrrev_i32_e32 v6, 11, v6
	v_add_u32_e32 v6, v6, v7
	v_mul_i32_i24_e32 v7, 0xffffef00, v6
	v_add3_u32 v7, s24, v7, v30
	s_movk_i32 s2, 0xff
	v_cmp_lt_i32_e32 vcc, s2, v7
	s_mov_b64 s[2:3], 0x3000
	v_ashrrev_i32_e32 v47, 31, v46
	v_cndmask_b32_e32 v6, 8, v6, vcc
	v_add_u32_e32 v6, s25, v6
	v_mul_i32_i24_e32 v6, 6, v6
	v_ashrrev_i32_e32 v7, 31, v6
	v_lshlrev_b64 v[6:7], 12, v[6:7]
	v_lshl_add_u64 v[6:7], s[16:17], 0, v[6:7]
	v_lshl_add_u64 v[48:49], v[6:7], 0, s[2:3]
	s_mov_b64 s[2:3], 0x4000
	v_lshl_add_u64 v[60:61], v[6:7], 0, s[2:3]
	v_lshl_add_u64 v[16:17], v[60:61], 0, v[0:1]
	global_load_dwordx4 v[6:9], v[34:35], off
	global_load_dwordx4 v[26:29], v[16:17], off
	v_lshl_add_u64 v[16:17], v[48:49], 0, v[0:1]
	global_load_dwordx4 v[56:59], v[16:17], off
	s_nop 1
	v_mov_b32_e32 v0, s26
	v_fmamk_f32 v0, v0, 0x3a800000, v183
	s_mov_b32 s2, 0x800000
	v_mul_f32_e32 v14, 0x4b800000, v0
	v_cmp_gt_f32_e32 vcc, s2, v0
	s_nop 1
	v_cndmask_b32_e32 v0, v0, v14, vcc
	v_rsq_f32_e32 v0, v0
	v_lshlrev_b64 v[14:15], 11, v[46:47]
	v_lshl_add_u64 v[46:47], v[36:37], 0, v[14:15]
	v_mul_f32_e32 v14, 0x45800000, v0
	v_cndmask_b32_e32 v0, v0, v14, vcc
	v_pk_mul_f32 v[14:15], v[24:25], v[0:1] op_sel_hi:[1,0]
	v_pk_mul_f32 v[16:17], v[22:23], v[0:1] op_sel_hi:[1,0]
	v_lshl_add_u64 v[22:23], v[48:49], 0, v[40:41]
	v_pk_mul_f32 v[20:21], v[20:21], v[0:1] op_sel_hi:[1,0]
	v_pk_mul_f32 v[18:19], v[18:19], v[0:1] op_sel_hi:[1,0]
	v_pk_mul_f32 v[12:13], v[12:13], v[0:1] op_sel_hi:[1,0]
	v_pk_mul_f32 v[10:11], v[10:11], v[0:1] op_sel_hi:[1,0]
	v_pk_mul_f32 v[4:5], v[4:5], v[0:1] op_sel_hi:[1,0]
	v_pk_mul_f32 v[2:3], v[2:3], v[0:1] op_sel_hi:[1,0]
	s_waitcnt vmcnt(2)
	v_pk_mul_f32 v[6:7], v[16:17], v[6:7]
	v_pk_mul_f32 v[8:9], v[14:15], v[8:9]
	s_waitcnt vmcnt(1)
	v_pk_add_f32 v[14:15], v[28:29], 1.0 op_sel_hi:[1,0]
	v_pk_add_f32 v[16:17], v[26:27], 1.0 op_sel_hi:[1,0]
	s_waitcnt vmcnt(0)
	v_pk_fma_f32 v[8:9], v[8:9], v[14:15], v[58:59]
	v_pk_fma_f32 v[6:7], v[6:7], v[16:17], v[56:57]
	v_bfe_u32 v16, v8, 16, 1
	v_bfe_u32 v14, v6, 16, 1
	v_bfe_u32 v15, v7, 16, 1
	v_bfe_u32 v17, v9, 16, 1
	v_add3_u32 v6, v6, v14, s31
	v_add3_u32 v8, v8, v16, s31
	v_add3_u32 v7, v7, v15, s31
	v_add3_u32 v9, v9, v17, s31
	v_lshrrev_b32_e32 v6, 16, v6
	v_lshrrev_b32_e32 v8, 16, v8
	v_and_or_b32 v6, v7, s0, v6
	v_and_or_b32 v7, v9, s0, v8
	global_store_dwordx2 v[46:47], v[6:7], off
	v_lshl_add_u64 v[14:15], v[60:61], 0, v[40:41]
	global_load_dwordx4 v[6:9], v[34:35], off offset:1024
	s_waitcnt vmcnt(0)
	v_pk_mul_f32 v[6:7], v[18:19], v[6:7]
	global_load_dwordx4 v[14:17], v[14:15], off
	v_pk_mul_f32 v[8:9], v[20:21], v[8:9]
	global_load_dwordx4 v[22:25], v[22:23], off
	v_lshl_add_u64 v[18:19], v[48:49], 0, v[42:43]
	s_waitcnt vmcnt(1)
	v_pk_add_f32 v[16:17], v[16:17], 1.0 op_sel_hi:[1,0]
	v_pk_add_f32 v[14:15], v[14:15], 1.0 op_sel_hi:[1,0]
	s_waitcnt vmcnt(0)
	v_pk_fma_f32 v[8:9], v[8:9], v[16:17], v[24:25]
	v_pk_fma_f32 v[6:7], v[6:7], v[14:15], v[22:23]
	v_bfe_u32 v16, v8, 16, 1
	v_bfe_u32 v14, v6, 16, 1
	v_bfe_u32 v15, v7, 16, 1
	v_bfe_u32 v17, v9, 16, 1
	v_add3_u32 v6, v6, v14, s31
	v_add3_u32 v8, v8, v16, s31
	v_add3_u32 v7, v7, v15, s31
	v_add3_u32 v9, v9, v17, s31
	v_lshrrev_b32_e32 v6, 16, v6
	v_lshrrev_b32_e32 v8, 16, v8
	v_and_or_b32 v6, v7, s0, v6
	v_and_or_b32 v7, v9, s0, v8
	global_store_dwordx2 v[46:47], v[6:7], off offset:512
	v_lshl_add_u64 v[14:15], v[60:61], 0, v[42:43]
	global_load_dwordx4 v[6:9], v[34:35], off offset:2048
	s_waitcnt vmcnt(0)
	v_pk_mul_f32 v[6:7], v[10:11], v[6:7]
	global_load_dwordx4 v[14:17], v[14:15], off
	v_pk_mul_f32 v[8:9], v[12:13], v[8:9]
	global_load_dwordx4 v[18:21], v[18:19], off
	s_waitcnt vmcnt(1)
	v_pk_add_f32 v[10:11], v[16:17], 1.0 op_sel_hi:[1,0]
	v_pk_add_f32 v[12:13], v[14:15], 1.0 op_sel_hi:[1,0]
	s_waitcnt vmcnt(0)
	v_pk_fma_f32 v[8:9], v[8:9], v[10:11], v[20:21]
	v_pk_fma_f32 v[6:7], v[6:7], v[12:13], v[18:19]
	v_bfe_u32 v12, v8, 16, 1
	v_bfe_u32 v10, v6, 16, 1
	v_bfe_u32 v11, v7, 16, 1
	v_bfe_u32 v13, v9, 16, 1
	v_add3_u32 v6, v6, v10, s31
	v_add3_u32 v8, v8, v12, s31
	v_add3_u32 v7, v7, v11, s31
	v_add3_u32 v9, v9, v13, s31
	v_lshrrev_b32_e32 v6, 16, v6
	v_lshrrev_b32_e32 v8, 16, v8
	v_and_or_b32 v6, v7, s0, v6
	v_and_or_b32 v7, v9, s0, v8
	global_store_dwordx2 v[46:47], v[6:7], off offset:1024
	v_lshl_add_u64 v[10:11], v[60:61], 0, v[44:45]
	global_load_dwordx4 v[6:9], v[34:35], off offset:3072
	v_lshl_add_u64 v[14:15], v[48:49], 0, v[44:45]
	global_load_dwordx4 v[10:13], v[10:11], off
	s_waitcnt vmcnt(1)
	v_pk_mul_f32 v[2:3], v[2:3], v[6:7]
	global_load_dwordx4 v[14:17], v[14:15], off
	v_pk_mul_f32 v[4:5], v[4:5], v[8:9]
	s_waitcnt vmcnt(1)
	v_pk_add_f32 v[6:7], v[12:13], 1.0 op_sel_hi:[1,0]
	v_pk_add_f32 v[8:9], v[10:11], 1.0 op_sel_hi:[1,0]
	s_waitcnt vmcnt(0)
	v_pk_fma_f32 v[4:5], v[4:5], v[6:7], v[16:17]
	v_pk_fma_f32 v[2:3], v[2:3], v[8:9], v[14:15]
	v_bfe_u32 v7, v4, 16, 1
	v_bfe_u32 v0, v2, 16, 1
	v_bfe_u32 v6, v3, 16, 1
	v_bfe_u32 v8, v5, 16, 1
	v_add3_u32 v0, v2, v0, s31
	v_add3_u32 v2, v3, v6, s31
	v_add3_u32 v3, v4, v7, s31
	v_add3_u32 v4, v5, v8, s31
	v_lshrrev_b32_e32 v0, 16, v0
	v_lshrrev_b32_e32 v3, 16, v3
	v_and_or_b32 v2, v2, s0, v0
	v_and_or_b32 v3, v4, s0, v3
	global_store_dwordx2 v[46:47], v[2:3], off offset:1536
	s_branch .LBB0_50

; #define LAS __attribute__((address_space(3)))
; DI const float* modp(const unsigned char* ws, int layer, int who, int idx) { return (const float*)(ws + WS_MOD) + ((size_t)(layer * 9 + who) * 6 + idx) * D; }
; DI void phase_rw_mix(int layer, int j, int q, LAS unsigned char* lds) {
;     ...
;         for (int rr = wave; rr < 19; rr += 8) {
;             const int t = t0 - 1 + rr;
;             if (t < 0 || t >= T) {
; #pragma unroll
;                 for (int jj = 0; jj < 4; ++jj) *(LAS f32x4*)(hs + rr * 1024 + 4 * lane + 256 * jj) = (f32x4){0.f, 0.f, 0.f, 0.f};
;             } else {
;                 const int who = t < LC ? 8 : b; const float* sh = modp(ws, layer, who, 0); const float* sc = modp(ws, layer, who, 1);
;                 const float* z = zrow(ws, outp, b * T + t); f32x4 v[4]; float ss = 0.f;
; #pragma unroll
;                 for (int jj = 0; jj < 4; ++jj) { v[jj] = *(const f32x4*)(z + 4 * lane + 256 * jj); ss += v[jj][0] * v[jj][0] + v[jj][1] * v[jj][1] + v[jj][2] * v[jj][2] + v[jj][3] * v[jj][3]; }
;                 const float rstd = rsqrtf(wave_sum(ss) * (1.f / D) + 1e-6f);
.LBB0_455:
	v_add3_u32 v5, s22, v21, 7
	s_movk_i32 s2, 0x1100
	v_cmp_gt_u32_e32 vcc, s2, v5
	s_and_saveexec_b64 s[2:3], vcc
	s_xor_b64 s[18:19], exec, s[2:3]
	s_cbranch_execz .LBB0_461
	v_add_u32_e32 v8, s23, v21
	v_add_u32_e32 v2, 7, v8
	s_mov_b32 s2, 0x78787879
	v_mul_hi_i32 v3, v2, s2
	v_lshrrev_b32_e32 v4, 31, v3
	v_ashrrev_i32_e32 v3, 11, v3
	v_add_u32_e32 v6, v3, v4
	s_movk_i32 s2, 0xef00
	v_mad_i32_i24 v2, v6, s2, v2
	s_movk_i32 s2, 0xff
	v_mul_i32_i24_e32 v7, 0xffffef00, v6
	v_cmp_lt_i32_e32 vcc, s2, v2
	v_mov_b64_e32 v[2:3], s[6:7]
	s_and_saveexec_b64 s[2:3], vcc
	s_xor_b64 s[2:3], exec, s[2:3]
	v_lshl_add_u32 v2, v6, 12, v7
	s_movk_i32 s28, 0xff07
	v_add3_u32 v4, v8, v2, s28
	v_mov_b64_e32 v[2:3], s[10:11]
	s_andn2_saveexec_b64 s[2:3], s[2:3]
	v_add_u32_e32 v4, s25, v25
	v_lshlrev_b32_e32 v6, 8, v6
	v_add3_u32 v4, v7, v4, v6
	s_or_b64 exec, exec, s[2:3]
	s_movk_i32 s2, 0xff
	v_cmp_lt_u32_e32 vcc, s2, v5
	v_mov_b32_e32 v5, s24
	v_readlane_b32 s2, v255, 31
	v_cndmask_b32_e32 v5, 8, v5, vcc
	s_mul_i32 s2, s2, 9
	v_add_u32_e32 v5, s2, v5
	v_mul_i32_i24_e32 v6, 6, v5
	v_ashrrev_i32_e32 v5, 31, v4
	v_lshlrev_b64 v[4:5], 12, v[4:5]
	v_lshl_add_u64 v[2:3], v[2:3], 0, v[4:5]
	v_lshl_add_u64 v[2:3], v[2:3], 0, v[0:1]
	global_load_dwordx4 v[26:29], v[2:3], off
	global_load_dwordx4 v[10:13], v[2:3], off offset:1024
	global_load_dwordx4 v[108:111], v[2:3], off offset:2048
	global_load_dwordx4 v[112:115], v[2:3], off offset:3072
	v_ashrrev_i32_e32 v7, 31, v6
	v_lshlrev_b64 v[6:7], 12, v[6:7]
	v_lshl_add_u64 v[14:15], s[12:13], 0, v[6:7]
	v_xor_b32_e32 v20, 1, v187
	s_mov_b64 s[2:3], 0x1000
	v_lshl_add_u64 v[18:19], v[14:15], 0, s[2:3]
	s_mov_b32 s2, 0x800000
	v_mov_b32_e32 v79, v1
	v_mov_b32_e32 v81, v1
	v_mov_b32_e32 v83, v1
	s_waitcnt vmcnt(3)
	v_mov_b32_e32 v6, v27
	s_waitcnt vmcnt(2)
	v_mov_b32_e32 v7, v11
	v_mov_b32_e32 v4, v26
	v_mov_b32_e32 v5, v10
	v_pk_mul_f32 v[6:7], v[6:7], v[6:7]
	s_nop 0
	v_pk_fma_f32 v[4:5], v[4:5], v[4:5], v[6:7]
	v_mov_b32_e32 v6, v28
	v_mov_b32_e32 v7, v12
	v_pk_fma_f32 v[4:5], v[6:7], v[6:7], v[4:5]
	v_mov_b32_e32 v6, v29
	v_mov_b32_e32 v7, v13
	v_pk_fma_f32 v[16:17], v[6:7], v[6:7], v[4:5]
	s_waitcnt vmcnt(0)
	v_mov_b64_e32 v[6:7], v[108:109]
	v_mov_b64_e32 v[8:9], v[110:111]
	v_mov_b64_e32 v[4:5], v[114:115]
	v_mov_b64_e32 v[2:3], v[112:113]
	v_add_f32_e32 v16, v16, v17
	v_and_b32_e32 v17, 64, v187
	v_add_u32_e32 v17, 64, v17
	v_cmp_lt_i32_e32 vcc, v20, v17
	s_waitcnt vmcnt(1)
	v_mov_b32_e32 v30, v7
	s_waitcnt vmcnt(0)
	v_mov_b32_e32 v31, v3
	v_mov_b32_e32 v22, v6
	v_mov_b32_e32 v23, v2
	v_pk_mul_f32 v[30:31], v[30:31], v[30:31]
	v_cndmask_b32_e32 v20, v187, v20, vcc
	v_pk_fma_f32 v[22:23], v[22:23], v[22:23], v[30:31]
	v_mov_b32_e32 v30, v8
	v_mov_b32_e32 v31, v4
	v_pk_fma_f32 v[22:23], v[30:31], v[30:31], v[22:23]
	v_mov_b32_e32 v30, v9
	v_mov_b32_e32 v31, v5
	v_pk_fma_f32 v[22:23], v[30:31], v[30:31], v[22:23]
	v_lshlrev_b32_e32 v20, 2, v20
	v_add_f32_e32 v16, v16, v22
	v_add_f32_e32 v16, v16, v23
	v_mov_b32_e32 v166, v16
	s_nop 1
	v_add_f32_dpp v166, v166, v166 row_shr:1 row_mask:0xf bank_mask:0xf
	s_nop 1
	v_add_f32_dpp v166, v166, v166 row_shr:2 row_mask:0xf bank_mask:0xf
	s_nop 1
	v_add_f32_dpp v166, v166, v166 row_shr:4 row_mask:0xf bank_mask:0xf
	s_nop 1
	v_add_f32_dpp v166, v166, v166 row_shr:8 row_mask:0xf bank_mask:0xf
	s_nop 1
	v_add_f32_dpp v166, v166, v166 row_bcast:15 row_mask:0xa bank_mask:0xf
	s_nop 1
	v_add_f32_dpp v166, v166, v166 row_bcast:31 row_mask:0xc bank_mask:0xf
	s_nop 0
	v_readlane_b32 s26, v166, 63
	global_load_dwordx4 v[30:33], v[52:53], off
	v_lshl_add_u64 v[22:23], v[14:15], 0, v[0:1]
	v_xor_b32_e32 v20, 2, v187
	v_cmp_lt_i32_e32 vcc, v20, v17
	s_nop 1
	v_cndmask_b32_e32 v20, v187, v20, vcc
	v_lshlrev_b32_e32 v20, 2, v20
	v_xor_b32_e32 v20, 4, v187
	v_cmp_lt_i32_e32 vcc, v20, v17
	s_nop 1
	v_cndmask_b32_e32 v20, v187, v20, vcc
	v_lshlrev_b32_e32 v20, 2, v20
	v_xor_b32_e32 v20, 8, v187
	v_cmp_lt_i32_e32 vcc, v20, v17
	s_nop 1
	v_cndmask_b32_e32 v20, v187, v20, vcc
	v_lshlrev_b32_e32 v20, 2, v20
	v_xor_b32_e32 v20, 16, v187
	v_cmp_lt_i32_e32 vcc, v20, v17
	s_nop 1
	v_cndmask_b32_e32 v20, v187, v20, vcc
	v_lshlrev_b32_e32 v20, 2, v20
	v_xor_b32_e32 v20, 32, v187
	v_cmp_lt_i32_e32 vcc, v20, v17
	s_nop 1
	v_cndmask_b32_e32 v17, v187, v20, vcc
	v_lshlrev_b32_e32 v17, 2, v17
	s_nop 1
	v_mov_b32_e32 v16, s26
	v_fmamk_f32 v16, v16, 0x3a800000, v183
	v_cmp_gt_f32_e32 vcc, s2, v16
	v_mul_f32_e32 v17, 0x4b800000, v16
	s_nop 0
	v_cndmask_b32_e32 v16, v16, v17, vcc
	v_rsq_f32_e32 v16, v16
	s_nop 0
	v_mul_f32_e32 v17, 0x45800000, v16
	v_cndmask_b32_e32 v20, v16, v17, vcc
	v_lshl_add_u64 v[16:17], v[18:19], 0, v[0:1]
	global_load_dwordx4 v[34:37], v[16:17], off
	v_pk_mul_f32 v[28:29], v[28:29], v[20:21] op_sel_hi:[1,0]
	global_load_dwordx4 v[14:17], v[22:23], off
	global_load_dwordx4 v[116:119], v[52:53], off offset:1024
	v_lshl_add_u64 v[152:153], v[18:19], 0, v[78:79]
	global_load_dwordx4 v[120:123], v[152:153], off
	global_load_dwordx4 v[124:127], v[22:23], off offset:1024
	global_load_dwordx4 v[128:131], v[52:53], off offset:2048
	v_lshl_add_u64 v[154:155], v[18:19], 0, v[80:81]
	global_load_dwordx4 v[132:135], v[154:155], off
	global_load_dwordx4 v[140:143], v[22:23], off offset:2048
	global_load_dwordx4 v[144:147], v[52:53], off offset:3072
	v_lshl_add_u64 v[156:157], v[18:19], 0, v[82:83]
	global_load_dwordx4 v[148:151], v[156:157], off
	global_load_dwordx4 v[158:161], v[22:23], off offset:3072
	v_pk_mul_f32 v[26:27], v[26:27], v[20:21] op_sel_hi:[1,0]
	s_waitcnt vmcnt(11)
; #define LAS __attribute__((address_space(3)))
; DI void phase_rw_mix(int layer, int j, int q, LAS unsigned char* lds) {
;     ...
; #pragma unroll
;                 for (int jj = 0; jj < 4; ++jj) { const int c = 4 * lane + 256 * jj;
;                     const f32x4 gg = *(const f32x4*)(g + c), a1 = *(const f32x4*)(sc + c), a0 = *(const f32x4*)(sh + c);
;                     f32x4 y = v[jj] * rstd * gg; y = y * (a1 + 1.f) + a0; *(LAS f32x4*)(hs + rr * 1024 + c) = y; }
	v_pk_mul_f32 v[28:29], v[32:33], v[28:29]
	v_pk_mul_f32 v[26:27], v[30:31], v[26:27]
	v_pk_mul_f32 v[12:13], v[12:13], v[20:21] op_sel_hi:[1,0]
	v_pk_mul_f32 v[10:11], v[10:11], v[20:21] op_sel_hi:[1,0]
	v_pk_mul_f32 v[8:9], v[8:9], v[20:21] op_sel_hi:[1,0]
	v_pk_mul_f32 v[6:7], v[6:7], v[20:21] op_sel_hi:[1,0]
	v_pk_mul_f32 v[4:5], v[4:5], v[20:21] op_sel_hi:[1,0]
	v_pk_mul_f32 v[2:3], v[2:3], v[20:21] op_sel_hi:[1,0]
	s_waitcnt vmcnt(10)
	v_pk_add_f32 v[30:31], v[36:37], 1.0 op_sel_hi:[1,0]
	v_pk_add_f32 v[32:33], v[34:35], 1.0 op_sel_hi:[1,0]
	s_waitcnt vmcnt(9)
	v_pk_fma_f32 v[16:17], v[30:31], v[28:29], v[16:17]
	v_pk_fma_f32 v[14:15], v[32:33], v[26:27], v[14:15]
	ds_write_b128 v24, v[14:17]
	s_waitcnt vmcnt(6)
	v_mov_b64_e32 v[14:15], v[116:117]
	v_mov_b64_e32 v[16:17], v[118:119]
	v_lshl_add_u64 v[26:27], v[18:19], 0, v[78:79]
	v_mov_b64_e32 v[26:27], v[120:121]
	v_mov_b64_e32 v[28:29], v[122:123]
	s_nop 0
	v_mov_b64_e32 v[30:31], v[124:125]
	v_mov_b64_e32 v[32:33], v[126:127]
	v_pk_mul_f32 v[10:11], v[14:15], v[10:11]
	v_pk_mul_f32 v[12:13], v[16:17], v[12:13]
	v_pk_add_f32 v[14:15], v[28:29], 1.0 op_sel_hi:[1,0]
	v_pk_add_f32 v[16:17], v[26:27], 1.0 op_sel_hi:[1,0]
	v_pk_fma_f32 v[12:13], v[14:15], v[12:13], v[32:33]
	v_pk_fma_f32 v[10:11], v[16:17], v[10:11], v[30:31]
	ds_write_b128 v24, v[10:13] offset:1024
	s_waitcnt vmcnt(3)
	v_mov_b64_e32 v[10:11], v[128:129]
	v_mov_b64_e32 v[12:13], v[130:131]
	v_lshl_add_u64 v[14:15], v[18:19], 0, v[80:81]
	v_mov_b64_e32 v[14:15], v[132:133]
	v_mov_b64_e32 v[16:17], v[134:135]
	s_nop 0
	v_mov_b64_e32 v[26:27], v[140:141]
	v_mov_b64_e32 v[28:29], v[142:143]
	v_pk_mul_f32 v[6:7], v[10:11], v[6:7]
	v_pk_mul_f32 v[8:9], v[12:13], v[8:9]
	v_pk_add_f32 v[10:11], v[16:17], 1.0 op_sel_hi:[1,0]
	v_pk_add_f32 v[12:13], v[14:15], 1.0 op_sel_hi:[1,0]
	v_pk_fma_f32 v[8:9], v[10:11], v[8:9], v[28:29]
	v_pk_fma_f32 v[6:7], v[12:13], v[6:7], v[26:27]
	ds_write_b128 v24, v[6:9] offset:2048
	s_waitcnt vmcnt(0)
	v_mov_b64_e32 v[14:15], v[144:145]
	v_mov_b64_e32 v[16:17], v[146:147]
	v_lshl_add_u64 v[6:7], v[18:19], 0, v[82:83]
	v_mov_b64_e32 v[6:7], v[148:149]
	v_mov_b64_e32 v[8:9], v[150:151]
	s_nop 0
	v_mov_b64_e32 v[10:11], v[158:159]
	v_mov_b64_e32 v[12:13], v[160:161]
	v_pk_mul_f32 v[2:3], v[14:15], v[2:3]
	v_pk_mul_f32 v[4:5], v[16:17], v[4:5]
	v_pk_add_f32 v[8:9], v[8:9], 1.0 op_sel_hi:[1,0]
	v_pk_add_f32 v[6:7], v[6:7], 1.0 op_sel_hi:[1,0]
	v_pk_fma_f32 v[4:5], v[4:5], v[8:9], v[12:13]
	v_pk_fma_f32 v[2:3], v[2:3], v[6:7], v[10:11]
	ds_write_b128 v24, v[2:5] offset:3072

; DI unsigned pk2(float lo, float hi) { return f2bf(lo) | (f2bf(hi) << 16); }
; #define BIDX() sgpr_opaque((int)__builtin_amdgcn_workgroup_id_x())
; DI const float* modp(const unsigned char* ws, int layer, int who, int idx) { return (const float*)(ws + WS_MOD) + ((size_t)(layer * 9 + who) * 6 + idx) * D; }
; DI void phase_norm(int layer, const float* g, int sidx, bf16_t* dst, bool first) {
;     ...
;     for (int m0 = BIDX() * 8 + wave; m0 < M; m0 += 2 * nw) {
;         const int m1 = m0 + nw; const bool has1 = m1 < M; const int m1c = has1 ? m1 : m0;
;         const float* z0 = zrow_src(zcs, zls, m0); const float* z1 = zrow_src(zcs, zls, m1c);
;         f32x4 v0[4], v1[4]; float ss0 = 0.f, ss1 = 0.f;
; #pragma unroll
;         for (int j = 0; j < 4; ++j) { v0[j] = *(const f32x4*)(z0 + 4 * lane + 256 * j); v1[j] = *(const f32x4*)(z1 + 4 * lane + 256 * j); }
; #pragma unroll
;         for (int j = 0; j < 4; ++j) { ss0 += v0[j][0] * v0[j][0] + v0[j][1] * v0[j][1] + v0[j][2] * v0[j][2] + v0[j][3] * v0[j][3]; ss1 += v1[j][0] * v1[j][0] + v1[j][1] * v1[j][1] + v1[j][2] * v1[j][2] + v1[j][3] * v1[j][3]; }
; #pragma unroll
;         for (int o = 1; o < 64; o <<= 1) { ss0 += __shfl_xor(ss0, o); ss1 += __shfl_xor(ss1, o); }
; #pragma unroll
;         for (int r = 0; r < 2; ++r) {
;             if (r == 1 && !has1) break;
;             const int m = r ? m1 : m0; const int b = m / T, t = m - b * T; const int who = t < LC ? 8 : b;
;             const float* sh = modp(ws, layer, who, sidx); const float* sc = modp(ws, layer, who, sidx + 1);
;             const float rstd = rsqrtf((r ? ss1 : ss0) * (1.f / D) + 1e-6f);
; #pragma unroll
;             for (int j = 0; j < 4; ++j) { const int c = 4 * lane + 256 * j;
;                 const f32x4 gg = *(const f32x4*)(g + c), s1 = *(const f32x4*)(sc + c), s0 = *(const f32x4*)(sh + c);
;                 f32x4 y = (r ? v1[j] : v0[j]) * rstd * gg; y = y * (s1 + 1.f) + s0;
;                 u32x2 w; w.x = pk2(y[0], y[1]); w.y = pk2(y[2], y[3]);
;                 *(u32x2*)(dst + (size_t)m * D + c) = w; }
.LBB0_759:
	s_mov_b32 s2, 0x78787879
	v_mul_hi_i32 v0, v30, s2
	v_lshrrev_b32_e32 v2, 31, v0
	v_ashrrev_i32_e32 v0, 11, v0
	v_add_u32_e32 v3, v0, v2
	s_movk_i32 s2, 0xef00
	v_mad_i32_i24 v0, v3, s2, v30
	s_movk_i32 s2, 0x100
	v_cmp_gt_i32_e64 s[4:5], s2, v0
	s_movk_i32 s2, 0xff
	v_cmp_lt_i32_e32 vcc, s2, v0
	s_and_saveexec_b64 s[2:3], vcc
	s_xor_b64 s[2:3], exec, s[2:3]
	v_mul_i32_i24_e32 v0, 0xffffef00, v3
	v_lshl_add_u32 v0, v3, 12, v0
	s_movk_i32 s6, 0xff00
	v_add3_u32 v6, v30, v0, s6
	s_or_saveexec_b64 s[2:3], s[2:3]
	s_waitcnt lgkmcnt(0)
	v_mov_b64_e32 v[8:9], s[12:13]
	s_xor_b64 exec, exec, s[2:3]
	v_lshl_add_u32 v6, v3, 8, v0
	v_mov_b64_e32 v[8:9], s[8:9]
	s_or_b64 exec, exec, s[2:3]
	v_add_u32_e32 v46, s22, v30
	s_mov_b32 s2, 0x8800
	v_cmp_gt_i32_e32 vcc, s2, v46
	s_mov_b32 s2, 0x78787879
	s_nop 0
	v_cndmask_b32_e32 v2, v30, v46, vcc
	v_mul_hi_i32 v0, v2, s2
	v_lshrrev_b32_e32 v4, 31, v0
	v_ashrrev_i32_e32 v0, 11, v0
	v_add_u32_e32 v0, v0, v4
	s_movk_i32 s2, 0xef00
	v_mad_i32_i24 v7, v0, s2, v2
	s_movk_i32 s2, 0xff
	v_cmp_lt_i32_e64 s[6:7], s2, v7
	s_and_saveexec_b64 s[2:3], s[6:7]
	s_xor_b64 s[2:3], exec, s[2:3]
	v_lshlrev_b32_e32 v0, 12, v0
	s_movk_i32 s6, 0xff00
	v_add3_u32 v2, v0, v7, s6
	s_or_saveexec_b64 s[2:3], s[2:3]
	v_mov_b64_e32 v[4:5], s[12:13]
	s_xor_b64 exec, exec, s[2:3]
	v_lshl_add_u32 v2, v0, 8, v7
	v_mov_b64_e32 v[4:5], s[8:9]
	s_or_b64 exec, exec, s[2:3]
	v_ashrrev_i32_e32 v7, 31, v6
	v_lshlrev_b64 v[6:7], 12, v[6:7]
	v_lshl_add_u64 v[6:7], v[8:9], 0, v[6:7]
	v_lshlrev_b32_e32 v0, 2, v32
	v_lshl_add_u64 v[6:7], v[6:7], 0, v[0:1]
	global_load_dwordx4 v[54:57], v[6:7], off
	global_load_dwordx4 v[26:29], v[6:7], off offset:1024
	global_load_dwordx4 v[14:17], v[6:7], off offset:2048
	s_nop 0
	global_load_dwordx4 v[6:9], v[6:7], off offset:3072
	v_cndmask_b32_e64 v3, v3, 8, s[4:5]
	v_add_u32_e32 v3, s23, v3
	v_mul_i32_i24_e32 v10, 6, v3
	v_ashrrev_i32_e32 v11, 31, v10
	v_lshlrev_b64 v[10:11], 12, v[10:11]
	v_lshl_add_u64 v[10:11], s[14:15], 0, v[10:11]
	s_mov_b64 s[2:3], 0x1000
	v_lshl_add_u64 v[70:71], v[10:11], 0, s[2:3]
	v_lshl_add_u64 v[12:13], v[70:71], 0, v[0:1]
	global_load_dwordx4 v[58:61], v[12:13], off
	global_load_dwordx4 v[62:65], v[34:35], off
	v_lshl_add_u64 v[72:73], v[10:11], 0, v[0:1]
	global_load_dwordx4 v[66:69], v[72:73], off
	s_mov_b32 s2, 0x800000
	v_mov_b32_e32 v41, v1
	s_waitcnt vmcnt(6)
	v_mov_b32_e32 v12, v55
	s_waitcnt vmcnt(5)
	v_mov_b32_e32 v13, v27
	v_mov_b32_e32 v10, v54
	v_mov_b32_e32 v11, v26
	s_waitcnt vmcnt(4)
	v_mov_b32_e32 v24, v15
	s_waitcnt vmcnt(3)
	v_mov_b32_e32 v25, v7
	v_pk_mul_f32 v[12:13], v[12:13], v[12:13]
	v_mov_b32_e32 v18, v56
	v_mov_b32_e32 v19, v28
	v_mov_b32_e32 v22, v14
	v_mov_b32_e32 v23, v6
	v_pk_mul_f32 v[24:25], v[24:25], v[24:25]
	v_pk_fma_f32 v[10:11], v[10:11], v[10:11], v[12:13]
	v_mov_b32_e32 v20, v57
	v_mov_b32_e32 v21, v29
	v_mov_b32_e32 v74, v16
	v_mov_b32_e32 v75, v8
	v_pk_fma_f32 v[12:13], v[22:23], v[22:23], v[24:25]
	v_pk_fma_f32 v[10:11], v[18:19], v[18:19], v[10:11]
	v_mov_b32_e32 v76, v17
	v_mov_b32_e32 v77, v9
	v_pk_fma_f32 v[12:13], v[74:75], v[74:75], v[12:13]
	v_pk_fma_f32 v[10:11], v[20:21], v[20:21], v[10:11]
	v_pk_fma_f32 v[12:13], v[76:77], v[76:77], v[12:13]
	v_add_f32_e32 v3, v10, v11
	v_add_f32_e32 v3, v3, v12
	v_add_f32_e32 v3, v3, v13
	v_mov_b32_e32 v96, v3
	s_nop 1
	v_add_f32_dpp v96, v96, v96 row_shr:1 row_mask:0xf bank_mask:0xf
	s_nop 1
	v_add_f32_dpp v96, v96, v96 row_shr:2 row_mask:0xf bank_mask:0xf
	s_nop 1
	v_add_f32_dpp v96, v96, v96 row_shr:4 row_mask:0xf bank_mask:0xf
	s_nop 1
	v_add_f32_dpp v96, v96, v96 row_shr:8 row_mask:0xf bank_mask:0xf
	s_nop 1
	v_add_f32_dpp v96, v96, v96 row_bcast:15 row_mask:0xa bank_mask:0xf
	s_nop 1
	v_add_f32_dpp v96, v96, v96 row_bcast:31 row_mask:0xc bank_mask:0xf
	s_nop 0
	v_readlane_b32 s26, v96, 63
	s_waitcnt vmcnt(2)
	v_pk_add_f32 v[60:61], v[60:61], 1.0 op_sel_hi:[1,0]
	v_pk_add_f32 v[58:59], v[58:59], 1.0 op_sel_hi:[1,0]
	v_ashrrev_i32_e32 v3, 31, v2
	v_lshlrev_b64 v[2:3], 12, v[2:3]
	v_lshl_add_u64 v[2:3], v[4:5], 0, v[2:3]
	v_lshl_add_u64 v[2:3], v[2:3], 0, v[0:1]
	global_load_dwordx4 v[22:25], v[2:3], off
	global_load_dwordx4 v[18:21], v[2:3], off offset:1024
	s_nop 1
	v_mov_b32_e32 v4, s26
	v_fmamk_f32 v4, v4, 0x3a800000, v183
	v_mul_f32_e32 v5, 0x4b800000, v4
	v_cmp_gt_f32_e64 s[4:5], s2, v4
	s_nop 1
	v_cndmask_b32_e64 v4, v4, v5, s[4:5]
	v_rsq_f32_e32 v31, v4
	global_load_dwordx4 v[10:13], v[2:3], off offset:2048
	s_nop 0
	global_load_dwordx4 v[2:5], v[2:3], off offset:3072
	v_mul_f32_e32 v43, 0x45800000, v31
	v_cndmask_b32_e64 v74, v31, v43, s[4:5]
	v_pk_mul_f32 v[56:57], v[56:57], v[74:75] op_sel_hi:[1,0]
	v_pk_mul_f32 v[54:55], v[54:55], v[74:75] op_sel_hi:[1,0]
	s_waitcnt vmcnt(5)
	v_pk_mul_f32 v[56:57], v[64:65], v[56:57]
	v_pk_mul_f32 v[54:55], v[62:63], v[54:55]
	s_waitcnt vmcnt(4)
	v_pk_fma_f32 v[56:57], v[60:61], v[56:57], v[68:69]
	v_pk_fma_f32 v[54:55], v[58:59], v[54:55], v[66:67]
	v_bfe_u32 v45, v56, 16, 1
	v_bfe_u32 v31, v54, 16, 1
	v_bfe_u32 v43, v55, 16, 1
	v_bfe_u32 v47, v57, 16, 1
	v_add3_u32 v31, v54, v31, s31
	v_add3_u32 v45, v56, v45, s31
	v_add3_u32 v43, v55, v43, s31
	v_add3_u32 v47, v57, v47, s31
	v_lshrrev_b32_e32 v31, 16, v31
	v_lshrrev_b32_e32 v45, 16, v45
	v_and_or_b32 v54, v43, s0, v31
	v_and_or_b32 v55, v47, s0, v45
	global_store_dwordx2 v[38:39], v[54:55], off
	global_load_dwordx4 v[54:57], v[34:35], off offset:1024
	v_lshl_add_u64 v[58:59], v[70:71], 0, v[40:41]
	global_load_dwordx4 v[58:61], v[58:59], off
	s_nop 0
	global_load_dwordx4 v[62:65], v[72:73], off offset:1024
	v_pk_mul_f32 v[28:29], v[28:29], v[74:75] op_sel_hi:[1,0]
	v_pk_mul_f32 v[26:27], v[26:27], v[74:75] op_sel_hi:[1,0]
	v_mov_b32_e32 v43, v1
	v_pk_mul_f32 v[16:17], v[16:17], v[74:75] op_sel_hi:[1,0]
	v_pk_mul_f32 v[14:15], v[14:15], v[74:75] op_sel_hi:[1,0]
	v_pk_mul_f32 v[8:9], v[8:9], v[74:75] op_sel_hi:[1,0]
	v_pk_mul_f32 v[6:7], v[6:7], v[74:75] op_sel_hi:[1,0]
	s_waitcnt vmcnt(2)
; DI unsigned pk2(float lo, float hi) { return f2bf(lo) | (f2bf(hi) << 16); }
; DI const float* modp(const unsigned char* ws, int layer, int who, int idx) { return (const float*)(ws + WS_MOD) + ((size_t)(layer * 9 + who) * 6 + idx) * D; }
; DI void phase_norm(int layer, const float* g, int sidx, bf16_t* dst, bool first) {
;     ...
;         for (int j = 0; j < 4; ++j) { v0[j] = *(const f32x4*)(z0 + 4 * lane + 256 * j); v1[j] = *(const f32x4*)(z1 + 4 * lane + 256 * j); }
; #pragma unroll
;         for (int j = 0; j < 4; ++j) { ss0 += v0[j][0] * v0[j][0] + v0[j][1] * v0[j][1] + v0[j][2] * v0[j][2] + v0[j][3] * v0[j][3]; ss1 += v1[j][0] * v1[j][0] + v1[j][1] * v1[j][1] + v1[j][2] * v1[j][2] + v1[j][3] * v1[j][3]; }
; #pragma unroll
;         for (int o = 1; o < 64; o <<= 1) { ss0 += __shfl_xor(ss0, o); ss1 += __shfl_xor(ss1, o); }
; #pragma unroll
;         for (int r = 0; r < 2; ++r) {
;             if (r == 1 && !has1) break;
;             const int m = r ? m1 : m0; const int b = m / T, t = m - b * T; const int who = t < LC ? 8 : b;
;             const float* sh = modp(ws, layer, who, sidx); const float* sc = modp(ws, layer, who, sidx + 1);
;             const float rstd = rsqrtf((r ? ss1 : ss0) * (1.f / D) + 1e-6f);
; #pragma unroll
;             for (int j = 0; j < 4; ++j) { const int c = 4 * lane + 256 * j;
;                 const f32x4 gg = *(const f32x4*)(g + c), s1 = *(const f32x4*)(sc + c), s0 = *(const f32x4*)(sh + c);
;                 f32x4 y = (r ? v1[j] : v0[j]) * rstd * gg; y = y * (s1 + 1.f) + s0;
;                 u32x2 w; w.x = pk2(y[0], y[1]); w.y = pk2(y[2], y[3]);
;                 *(u32x2*)(dst + (size_t)m * D + c) = w; }
	v_pk_mul_f32 v[26:27], v[54:55], v[26:27]
	v_pk_mul_f32 v[28:29], v[56:57], v[28:29]
	s_waitcnt vmcnt(1)
	v_pk_add_f32 v[54:55], v[60:61], 1.0 op_sel_hi:[1,0]
	v_pk_add_f32 v[56:57], v[58:59], 1.0 op_sel_hi:[1,0]
	s_waitcnt vmcnt(0)
	v_pk_fma_f32 v[28:29], v[54:55], v[28:29], v[64:65]
	v_pk_fma_f32 v[26:27], v[56:57], v[26:27], v[62:63]
	v_bfe_u32 v47, v28, 16, 1
	v_bfe_u32 v31, v26, 16, 1
	v_bfe_u32 v45, v27, 16, 1
	v_bfe_u32 v53, v29, 16, 1
	v_add3_u32 v26, v26, v31, s31
	v_add3_u32 v28, v28, v47, s31
	v_add3_u32 v27, v27, v45, s31
	v_add3_u32 v29, v29, v53, s31
	v_lshrrev_b32_e32 v26, 16, v26
	v_lshrrev_b32_e32 v28, 16, v28
	v_and_or_b32 v26, v27, s0, v26
	v_and_or_b32 v27, v29, s0, v28
	global_store_dwordx2 v[38:39], v[26:27], off offset:512
	global_load_dwordx4 v[26:29], v[34:35], off offset:2048
	v_lshl_add_u64 v[54:55], v[70:71], 0, v[42:43]
	global_load_dwordx4 v[54:57], v[54:55], off
	s_nop 0
	global_load_dwordx4 v[58:61], v[72:73], off offset:2048
	v_mov_b32_e32 v45, v1
	s_waitcnt vmcnt(2)
	v_pk_mul_f32 v[14:15], v[26:27], v[14:15]
	v_pk_mul_f32 v[16:17], v[28:29], v[16:17]
	s_waitcnt vmcnt(1)
	v_pk_add_f32 v[26:27], v[56:57], 1.0 op_sel_hi:[1,0]
	v_pk_add_f32 v[28:29], v[54:55], 1.0 op_sel_hi:[1,0]
	s_waitcnt vmcnt(0)
	v_pk_fma_f32 v[16:17], v[26:27], v[16:17], v[60:61]
	v_pk_fma_f32 v[14:15], v[28:29], v[14:15], v[58:59]
	v_bfe_u32 v28, v16, 16, 1
	v_bfe_u32 v26, v14, 16, 1
	v_bfe_u32 v27, v15, 16, 1
	v_bfe_u32 v29, v17, 16, 1
	v_add3_u32 v14, v14, v26, s31
	v_add3_u32 v16, v16, v28, s31
	v_add3_u32 v15, v15, v27, s31
	v_add3_u32 v17, v17, v29, s31
	v_lshrrev_b32_e32 v14, 16, v14
	v_lshrrev_b32_e32 v16, 16, v16
	v_and_or_b32 v14, v15, s0, v14
	v_and_or_b32 v15, v17, s0, v16
	global_store_dwordx2 v[38:39], v[14:15], off offset:1024
	global_load_dwordx4 v[26:29], v[34:35], off offset:3072
	v_lshl_add_u64 v[14:15], v[70:71], 0, v[44:45]
	global_load_dwordx4 v[54:57], v[14:15], off
	global_load_dwordx4 v[58:61], v[72:73], off offset:3072
	v_mul_f32_e32 v14, v23, v23
	v_mul_f32_e32 v15, v19, v19
	v_mul_f32_e32 v16, v11, v11
	v_fmac_f32_e32 v14, v22, v22
	v_fmac_f32_e32 v15, v18, v18
	v_mul_f32_e32 v17, v3, v3
	v_fmac_f32_e32 v16, v10, v10
	v_fmac_f32_e32 v14, v24, v24
	v_fmac_f32_e32 v15, v20, v20
	v_fmac_f32_e32 v17, v2, v2
	v_fmac_f32_e32 v16, v12, v12
	v_fmac_f32_e32 v14, v25, v25
	v_fmac_f32_e32 v15, v21, v21
	v_fmac_f32_e32 v17, v4, v4
	v_fmac_f32_e32 v16, v13, v13
	v_add_f32_e32 v14, v14, v15
	v_fmac_f32_e32 v17, v5, v5
	v_add_f32_e32 v14, v14, v16
	v_add_f32_e32 v14, v14, v17
	v_mov_b32_e32 v96, v14
	s_nop 1
	v_add_f32_dpp v96, v96, v96 row_shr:1 row_mask:0xf bank_mask:0xf
	s_nop 1
	v_add_f32_dpp v96, v96, v96 row_shr:2 row_mask:0xf bank_mask:0xf
	s_nop 1
	v_add_f32_dpp v96, v96, v96 row_shr:4 row_mask:0xf bank_mask:0xf
	s_nop 1
	v_add_f32_dpp v96, v96, v96 row_shr:8 row_mask:0xf bank_mask:0xf
	s_nop 1
	v_add_f32_dpp v96, v96, v96 row_bcast:15 row_mask:0xa bank_mask:0xf
	s_nop 1
	v_add_f32_dpp v96, v96, v96 row_bcast:31 row_mask:0xc bank_mask:0xf
	s_nop 0
	v_readlane_b32 s26, v96, 63
	s_waitcnt vmcnt(2)
	v_pk_mul_f32 v[6:7], v[6:7], v[26:27]
	v_pk_mul_f32 v[8:9], v[8:9], v[28:29]
	s_waitcnt vmcnt(1)
	v_pk_add_f32 v[16:17], v[56:57], 1.0 op_sel_hi:[1,0]
	v_pk_add_f32 v[26:27], v[54:55], 1.0 op_sel_hi:[1,0]
	s_waitcnt vmcnt(0)
	v_pk_fma_f32 v[8:9], v[8:9], v[16:17], v[60:61]
	v_pk_fma_f32 v[6:7], v[6:7], v[26:27], v[58:59]
	v_bfe_u32 v26, v8, 16, 1
	v_bfe_u32 v16, v6, 16, 1
	v_bfe_u32 v17, v7, 16, 1
	v_bfe_u32 v27, v9, 16, 1
	v_add3_u32 v6, v6, v16, s31
	v_add3_u32 v8, v8, v26, s31
	v_add3_u32 v7, v7, v17, s31
	v_add3_u32 v9, v9, v27, s31
	v_lshrrev_b32_e32 v6, 16, v6
	v_lshrrev_b32_e32 v8, 16, v8
	v_and_or_b32 v6, v7, s0, v6
	v_and_or_b32 v7, v9, s0, v8
	global_store_dwordx2 v[38:39], v[6:7], off offset:1536
	s_and_saveexec_b64 s[4:5], vcc
	s_cbranch_execz .LBB0_758
; DI unsigned pk2(float lo, float hi) { return f2bf(lo) | (f2bf(hi) << 16); }
; DI const float* modp(const unsigned char* ws, int layer, int who, int idx) { return (const float*)(ws + WS_MOD) + ((size_t)(layer * 9 + who) * 6 + idx) * D; }
; DI void phase_norm(int layer, const float* g, int sidx, bf16_t* dst, bool first) {
;     ...
;         for (int r = 0; r < 2; ++r) {
;             if (r == 1 && !has1) break;
;             const int m = r ? m1 : m0; const int b = m / T, t = m - b * T; const int who = t < LC ? 8 : b;
;             const float* sh = modp(ws, layer, who, sidx); const float* sc = modp(ws, layer, who, sidx + 1);
;             const float rstd = rsqrtf((r ? ss1 : ss0) * (1.f / D) + 1e-6f);
; #pragma unroll
;             for (int j = 0; j < 4; ++j) { const int c = 4 * lane + 256 * j;
;                 const f32x4 gg = *(const f32x4*)(g + c), s1 = *(const f32x4*)(sc + c), s0 = *(const f32x4*)(sh + c);
;                 f32x4 y = (r ? v1[j] : v0[j]) * rstd * gg; y = y * (s1 + 1.f) + s0;
;                 u32x2 w; w.x = pk2(y[0], y[1]); w.y = pk2(y[2], y[3]);
;                 *(u32x2*)(dst + (size_t)m * D + c) = w; }
	s_mov_b32 s2, 0x78787879
	v_mul_hi_i32 v6, v46, s2
	v_lshrrev_b32_e32 v7, 31, v6
	v_ashrrev_i32_e32 v6, 11, v6
	v_add_u32_e32 v6, v6, v7
	v_mul_i32_i24_e32 v7, 0xffffef00, v6
	v_add3_u32 v7, s22, v7, v30
	s_movk_i32 s2, 0xff
	v_cmp_lt_i32_e32 vcc, s2, v7
	s_mov_b64 s[2:3], 0x1000
	v_ashrrev_i32_e32 v47, 31, v46
	v_cndmask_b32_e32 v6, 8, v6, vcc
	v_add_u32_e32 v6, s23, v6
	v_mul_i32_i24_e32 v6, 6, v6
	v_ashrrev_i32_e32 v7, 31, v6
	v_lshlrev_b64 v[6:7], 12, v[6:7]
	v_lshl_add_u64 v[16:17], s[14:15], 0, v[6:7]
	v_lshl_add_u64 v[58:59], v[16:17], 0, s[2:3]
	v_lshl_add_u64 v[26:27], v[58:59], 0, v[0:1]
	global_load_dwordx4 v[6:9], v[34:35], off
	v_lshl_add_u64 v[60:61], v[16:17], 0, v[0:1]
	global_load_dwordx4 v[26:29], v[26:27], off
	s_nop 1
	v_mov_b32_e32 v0, s26
	global_load_dwordx4 v[54:57], v[60:61], off
	v_fmamk_f32 v0, v0, 0x3a800000, v183
	s_mov_b32 s2, 0x800000
	v_mul_f32_e32 v14, 0x4b800000, v0
	v_cmp_gt_f32_e32 vcc, s2, v0
	s_nop 1
	v_cndmask_b32_e32 v0, v0, v14, vcc
	v_rsq_f32_e32 v0, v0
	v_lshlrev_b64 v[14:15], 11, v[46:47]
	v_lshl_add_u64 v[46:47], v[36:37], 0, v[14:15]
	v_mul_f32_e32 v14, 0x45800000, v0
	v_cndmask_b32_e32 v0, v0, v14, vcc
	v_pk_mul_f32 v[14:15], v[24:25], v[0:1] op_sel_hi:[1,0]
	v_pk_mul_f32 v[16:17], v[22:23], v[0:1] op_sel_hi:[1,0]
	v_pk_mul_f32 v[20:21], v[20:21], v[0:1] op_sel_hi:[1,0]
	v_pk_mul_f32 v[18:19], v[18:19], v[0:1] op_sel_hi:[1,0]
	v_pk_mul_f32 v[12:13], v[12:13], v[0:1] op_sel_hi:[1,0]
	v_pk_mul_f32 v[10:11], v[10:11], v[0:1] op_sel_hi:[1,0]
	v_pk_mul_f32 v[4:5], v[4:5], v[0:1] op_sel_hi:[1,0]
	v_pk_mul_f32 v[2:3], v[2:3], v[0:1] op_sel_hi:[1,0]
	s_waitcnt vmcnt(2)
	v_pk_mul_f32 v[6:7], v[16:17], v[6:7]
	v_pk_mul_f32 v[8:9], v[14:15], v[8:9]
	s_waitcnt vmcnt(1)
	v_pk_add_f32 v[14:15], v[28:29], 1.0 op_sel_hi:[1,0]
	v_pk_add_f32 v[16:17], v[26:27], 1.0 op_sel_hi:[1,0]
	s_waitcnt vmcnt(0)
	v_pk_fma_f32 v[8:9], v[8:9], v[14:15], v[56:57]
	v_pk_fma_f32 v[6:7], v[6:7], v[16:17], v[54:55]
	v_bfe_u32 v16, v8, 16, 1
	v_bfe_u32 v14, v6, 16, 1
	v_bfe_u32 v15, v7, 16, 1
	v_bfe_u32 v17, v9, 16, 1
	v_add3_u32 v6, v6, v14, s31
	v_add3_u32 v8, v8, v16, s31
	v_add3_u32 v7, v7, v15, s31
	v_add3_u32 v9, v9, v17, s31
	v_lshrrev_b32_e32 v6, 16, v6
	v_lshrrev_b32_e32 v8, 16, v8
	v_and_or_b32 v6, v7, s0, v6
	v_and_or_b32 v7, v9, s0, v8
	global_store_dwordx2 v[46:47], v[6:7], off
	global_load_dwordx4 v[6:9], v[34:35], off offset:1024
	v_lshl_add_u64 v[14:15], v[58:59], 0, v[40:41]
	global_load_dwordx4 v[14:17], v[14:15], off
	s_nop 0
	global_load_dwordx4 v[22:25], v[60:61], off offset:1024
	s_waitcnt vmcnt(2)
	v_pk_mul_f32 v[6:7], v[18:19], v[6:7]
	v_pk_mul_f32 v[8:9], v[20:21], v[8:9]
	s_waitcnt vmcnt(1)
	v_pk_add_f32 v[16:17], v[16:17], 1.0 op_sel_hi:[1,0]
	v_pk_add_f32 v[14:15], v[14:15], 1.0 op_sel_hi:[1,0]
	s_waitcnt vmcnt(0)
	v_pk_fma_f32 v[8:9], v[8:9], v[16:17], v[24:25]
	v_pk_fma_f32 v[6:7], v[6:7], v[14:15], v[22:23]
	v_bfe_u32 v16, v8, 16, 1
	v_bfe_u32 v14, v6, 16, 1
	v_bfe_u32 v15, v7, 16, 1
	v_bfe_u32 v17, v9, 16, 1
	v_add3_u32 v6, v6, v14, s31
	v_add3_u32 v8, v8, v16, s31
	v_add3_u32 v7, v7, v15, s31
	v_add3_u32 v9, v9, v17, s31
	v_lshrrev_b32_e32 v6, 16, v6
	v_lshrrev_b32_e32 v8, 16, v8
	v_and_or_b32 v6, v7, s0, v6
	v_and_or_b32 v7, v9, s0, v8
	global_store_dwordx2 v[46:47], v[6:7], off offset:512
	global_load_dwordx4 v[6:9], v[34:35], off offset:2048
	v_lshl_add_u64 v[14:15], v[58:59], 0, v[42:43]
	global_load_dwordx4 v[14:17], v[14:15], off
	s_nop 0
	global_load_dwordx4 v[18:21], v[60:61], off offset:2048
	s_waitcnt vmcnt(2)
	v_pk_mul_f32 v[6:7], v[10:11], v[6:7]
	v_pk_mul_f32 v[8:9], v[12:13], v[8:9]
	s_waitcnt vmcnt(1)
	v_pk_add_f32 v[10:11], v[16:17], 1.0 op_sel_hi:[1,0]
	v_pk_add_f32 v[12:13], v[14:15], 1.0 op_sel_hi:[1,0]
	s_waitcnt vmcnt(0)
	v_pk_fma_f32 v[8:9], v[8:9], v[10:11], v[20:21]
	v_pk_fma_f32 v[6:7], v[6:7], v[12:13], v[18:19]
	v_bfe_u32 v12, v8, 16, 1
	v_bfe_u32 v10, v6, 16, 1
	v_bfe_u32 v11, v7, 16, 1
	v_bfe_u32 v13, v9, 16, 1
	v_add3_u32 v6, v6, v10, s31
	v_add3_u32 v8, v8, v12, s31
	v_add3_u32 v7, v7, v11, s31
	v_add3_u32 v9, v9, v13, s31
	v_lshrrev_b32_e32 v6, 16, v6
	v_lshrrev_b32_e32 v8, 16, v8
	v_and_or_b32 v6, v7, s0, v6
	v_and_or_b32 v7, v9, s0, v8
	global_store_dwordx2 v[46:47], v[6:7], off offset:1024
	global_load_dwordx4 v[6:9], v[34:35], off offset:3072
	v_lshl_add_u64 v[10:11], v[58:59], 0, v[44:45]
	global_load_dwordx4 v[10:13], v[10:11], off
	s_nop 0
	global_load_dwordx4 v[14:17], v[60:61], off offset:3072
	s_waitcnt vmcnt(2)
	v_pk_mul_f32 v[2:3], v[2:3], v[6:7]
	v_pk_mul_f32 v[4:5], v[4:5], v[8:9]
	s_waitcnt vmcnt(1)
	v_pk_add_f32 v[6:7], v[12:13], 1.0 op_sel_hi:[1,0]
	v_pk_add_f32 v[8:9], v[10:11], 1.0 op_sel_hi:[1,0]
	s_waitcnt vmcnt(0)
	v_pk_fma_f32 v[4:5], v[4:5], v[6:7], v[16:17]
	v_pk_fma_f32 v[2:3], v[2:3], v[8:9], v[14:15]
	v_bfe_u32 v7, v4, 16, 1
	v_bfe_u32 v0, v2, 16, 1
	v_bfe_u32 v6, v3, 16, 1
	v_bfe_u32 v8, v5, 16, 1
	v_add3_u32 v0, v2, v0, s31
	v_add3_u32 v2, v3, v6, s31
	v_add3_u32 v3, v4, v7, s31
	v_add3_u32 v4, v5, v8, s31
	v_lshrrev_b32_e32 v0, 16, v0
	v_lshrrev_b32_e32 v3, 16, v3
	v_and_or_b32 v2, v2, s0, v0
	v_and_or_b32 v3, v4, s0, v3
	global_store_dwordx2 v[46:47], v[2:3], off offset:1536
	s_branch .LBB0_758
